# EpiMlpIn v2 with nt output stores
# baseline (speedup 1.0000x reference)
; __device__ __forceinline__ u32x4 pack8(const f32x4 v0, const f32x4 v1) { u32x4 w; w.x = cvt_pk_bf16(v0[0], v0[1]); w.y = cvt_pk_bf16(v0[2], v0[3]); w.z = cvt_pk_bf16(v1[0], v1[1]); w.w = cvt_pk_bf16(v1[2], v1[3]); return w; }
; __device__ __forceinline__ void row_rs8(float (&rs)[8], const float* ssq, int row0, int fq) {
;     f32x4 p[8];
; #pragma unroll
;     for (int i = 0; i < 8; ++i) p[i] = *(const f32x4*)(ssq + (size_t)(row0 + (i >> 2) * HALF + (i & 3) * 16) * 16 + 4 * fq);
; #pragma unroll
;     for (int i = 0; i < 8; ++i) { float s = (p[i][0] + p[i][1]) + (p[i][2] + p[i][3]); s += __shfl_xor(s, 16); s += __shfl_xor(s, 32); rs[i] = __builtin_amdgcn_rsqf(s * (1.0f / DMODEL) + RMS_EPS); }
;     __device__ __forceinline__ void operator()(const f32x4 (&acc)[2][2][4][2], const Unit& u, int wr, int wc, int fr, int fq) const {
;         const int row0 = u.pm * BM + wr * 64 + fr, col0 = u.pn * BM + wc * 32 + 8 * fq;
;         float rs[8]; row_rs8(rs, ssq, row0, fq);
; #pragma unroll
;         for (int ai = 0; ai < 2; ++ai)
; #pragma unroll
;             for (int m = 0; m < 4; ++m) { const int row = row0 + ai * HALF + m * 16; const float r = rs[ai * 4 + m];
;                 bf16_t* rowp = O + (size_t)row * ldc + col0;
; #pragma unroll
;                 for (int bj = 0; bj < 2; ++bj) { f32x4 v0 = acc[ai][bj][m][0] * r, v1 = acc[ai][bj][m][1] * r;
; #pragma unroll
;                     for (int e = 0; e < 4; ++e) { const float a = fmaxf(v0[e], 0.f), b = fmaxf(v1[e], 0.f); v0[e] = a * a; v1[e] = b * b; }
;                     *(u32x4*)(rowp + bj * HALF) = pack8(v0, v1); } }
.LBB0_614:
	v_readfirstlane_b32 s11, v192
	v_and_b32_e32 v176, 15, v192
	s_lshl_b32 s13, s22, 8
	s_lshr_b32 s22, s11, 8
	s_lshl_b32 s22, s22, 6
	s_add_i32 s22, s22, s13
	v_add_u32_e32 v176, s22, v176
	v_bfe_u32 v177, v192, 4, 2
	s_lshr_b32 s11, s11, 1
	s_and_b32 s11, s11, 0x60
	s_lshl_b32 s13, s20, 8
	s_or_b32 s11, s11, s13
	v_lshl_or_b32 v178, v177, 3, s11
	v_lshlrev_b32_e32 v172, 13, v176
	v_lshl_add_u32 v172, v178, 1, v172
	v_lshlrev_b32_e32 v173, 6, v176
	v_lshl_add_u32 v173, v177, 4, v173
	global_load_dwordx4 v[128:131], v173, s[6:7]
	v_add_u32_e32 v178, 0x400, v173
	global_load_dwordx4 v[132:135], v178, s[6:7]
	v_add_u32_e32 v178, 0x800, v173
	global_load_dwordx4 v[136:139], v178, s[6:7]
	v_add_u32_e32 v178, 0xc00, v173
	global_load_dwordx4 v[140:143], v178, s[6:7]
	v_add_u32_e32 v178, 0x2000, v173
	global_load_dwordx4 v[144:147], v178, s[6:7]
	v_add_u32_e32 v178, 0x2400, v173
	global_load_dwordx4 v[148:151], v178, s[6:7]
	v_add_u32_e32 v178, 0x2800, v173
	global_load_dwordx4 v[164:167], v178, s[6:7]
	v_add_u32_e32 v178, 0x2c00, v173
	global_load_dwordx4 v[168:171], v178, s[6:7]
	v_xor_b32_e32 v174, 16, v241
	v_xor_b32_e32 v175, 32, v241
	v_lshlrev_b32_e32 v174, 2, v174
	v_lshlrev_b32_e32 v175, 2, v175
	s_waitcnt vmcnt(7)
	v_add_f32_e32 v176, v128, v129
	v_add_f32_e32 v177, v130, v131
	v_add_f32_e32 v176, v176, v177
	ds_bpermute_b32 v177, v174, v176
	s_waitcnt lgkmcnt(0)
	v_add_f32_e32 v176, v176, v177
	ds_bpermute_b32 v177, v175, v176
	v_mov_b32_e32 v178, v172
	s_waitcnt lgkmcnt(0)
	v_add_f32_e32 v176, v176, v177
	v_fmamk_f32 v176, v176, 0x3a800000, v193
	v_rsq_f32_e32 v180, v176
	s_nop 0
	v_pk_mul_f32 v[124:125], v[124:125], v[180:181] op_sel_hi:[1,0]
	v_pk_mul_f32 v[126:127], v[126:127], v[180:181] op_sel_hi:[1,0]
	v_pk_mul_f32 v[120:121], v[120:121], v[180:181] op_sel_hi:[1,0]
	v_pk_mul_f32 v[122:123], v[122:123], v[180:181] op_sel_hi:[1,0]
	v_max_f32_e32 v124, 0, v124
	v_max_f32_e32 v125, 0, v125
	v_max_f32_e32 v126, 0, v126
	v_max_f32_e32 v127, 0, v127
	v_max_f32_e32 v120, 0, v120
	v_max_f32_e32 v121, 0, v121
	v_max_f32_e32 v122, 0, v122
	v_max_f32_e32 v123, 0, v123
	v_pk_mul_f32 v[124:125], v[124:125], v[124:125]
	v_pk_mul_f32 v[126:127], v[126:127], v[126:127]
	v_pk_mul_f32 v[120:121], v[120:121], v[120:121]
	v_pk_mul_f32 v[122:123], v[122:123], v[122:123]
	v_cvt_pk_bf16_f32 v124, v124, v125
	v_cvt_pk_bf16_f32 v125, v126, v127
	v_cvt_pk_bf16_f32 v126, v120, v121
	v_cvt_pk_bf16_f32 v127, v122, v123
	global_store_dwordx4 v178, v[124:127], s[0:1] nt
	v_pk_mul_f32 v[116:117], v[116:117], v[180:181] op_sel_hi:[1,0]
	v_pk_mul_f32 v[118:119], v[118:119], v[180:181] op_sel_hi:[1,0]
	v_pk_mul_f32 v[112:113], v[112:113], v[180:181] op_sel_hi:[1,0]
	v_pk_mul_f32 v[114:115], v[114:115], v[180:181] op_sel_hi:[1,0]
	v_max_f32_e32 v116, 0, v116
	v_max_f32_e32 v117, 0, v117
	v_max_f32_e32 v118, 0, v118
	v_max_f32_e32 v119, 0, v119
	v_max_f32_e32 v112, 0, v112
	v_max_f32_e32 v113, 0, v113
	v_max_f32_e32 v114, 0, v114
	v_max_f32_e32 v115, 0, v115
	v_pk_mul_f32 v[116:117], v[116:117], v[116:117]
	v_pk_mul_f32 v[118:119], v[118:119], v[118:119]
	v_pk_mul_f32 v[112:113], v[112:113], v[112:113]
	v_pk_mul_f32 v[114:115], v[114:115], v[114:115]
	v_cvt_pk_bf16_f32 v116, v116, v117
	v_cvt_pk_bf16_f32 v117, v118, v119
	v_cvt_pk_bf16_f32 v118, v112, v113
	v_cvt_pk_bf16_f32 v119, v114, v115
	global_store_dwordx4 v178, v[116:119], s[0:1] offset:256 nt
	s_waitcnt vmcnt(8)
	v_add_f32_e32 v176, v132, v133
	v_add_f32_e32 v177, v134, v135
	v_add_f32_e32 v176, v176, v177
	ds_bpermute_b32 v177, v174, v176
	s_waitcnt lgkmcnt(0)
	v_add_f32_e32 v176, v176, v177
	ds_bpermute_b32 v177, v175, v176
	v_add_u32_e32 v178, 0x20000, v172
	s_waitcnt lgkmcnt(0)
	v_add_f32_e32 v176, v176, v177
	v_fmamk_f32 v176, v176, 0x3a800000, v193
	v_rsq_f32_e32 v180, v176
	s_nop 0
	v_pk_mul_f32 v[108:109], v[108:109], v[180:181] op_sel_hi:[1,0]
	v_pk_mul_f32 v[110:111], v[110:111], v[180:181] op_sel_hi:[1,0]
	v_pk_mul_f32 v[104:105], v[104:105], v[180:181] op_sel_hi:[1,0]
	v_pk_mul_f32 v[106:107], v[106:107], v[180:181] op_sel_hi:[1,0]
	v_max_f32_e32 v108, 0, v108
	v_max_f32_e32 v109, 0, v109
	v_max_f32_e32 v110, 0, v110
	v_max_f32_e32 v111, 0, v111
	v_max_f32_e32 v104, 0, v104
	v_max_f32_e32 v105, 0, v105
	v_max_f32_e32 v106, 0, v106
	v_max_f32_e32 v107, 0, v107
	v_pk_mul_f32 v[108:109], v[108:109], v[108:109]
	v_pk_mul_f32 v[110:111], v[110:111], v[110:111]
	v_pk_mul_f32 v[104:105], v[104:105], v[104:105]
	v_pk_mul_f32 v[106:107], v[106:107], v[106:107]
	v_cvt_pk_bf16_f32 v108, v108, v109
	v_cvt_pk_bf16_f32 v109, v110, v111
	v_cvt_pk_bf16_f32 v110, v104, v105
	v_cvt_pk_bf16_f32 v111, v106, v107
	global_store_dwordx4 v178, v[108:111], s[0:1] nt
	v_pk_mul_f32 v[100:101], v[100:101], v[180:181] op_sel_hi:[1,0]
	v_pk_mul_f32 v[102:103], v[102:103], v[180:181] op_sel_hi:[1,0]
	v_pk_mul_f32 v[96:97], v[96:97], v[180:181] op_sel_hi:[1,0]
	v_pk_mul_f32 v[98:99], v[98:99], v[180:181] op_sel_hi:[1,0]
	v_max_f32_e32 v100, 0, v100
	v_max_f32_e32 v101, 0, v101
	v_max_f32_e32 v102, 0, v102
	v_max_f32_e32 v103, 0, v103
	v_max_f32_e32 v96, 0, v96
	v_max_f32_e32 v97, 0, v97
	v_max_f32_e32 v98, 0, v98
	v_max_f32_e32 v99, 0, v99
	v_pk_mul_f32 v[100:101], v[100:101], v[100:101]
	v_pk_mul_f32 v[102:103], v[102:103], v[102:103]
	v_pk_mul_f32 v[96:97], v[96:97], v[96:97]
	v_pk_mul_f32 v[98:99], v[98:99], v[98:99]
	v_cvt_pk_bf16_f32 v100, v100, v101
	v_cvt_pk_bf16_f32 v101, v102, v103
	v_cvt_pk_bf16_f32 v102, v96, v97
	v_cvt_pk_bf16_f32 v103, v98, v99
	global_store_dwordx4 v178, v[100:103], s[0:1] offset:256 nt
	s_waitcnt vmcnt(9)
; __device__ __forceinline__ u32x4 pack8(const f32x4 v0, const f32x4 v1) { u32x4 w; w.x = cvt_pk_bf16(v0[0], v0[1]); w.y = cvt_pk_bf16(v0[2], v0[3]); w.z = cvt_pk_bf16(v1[0], v1[1]); w.w = cvt_pk_bf16(v1[2], v1[3]); return w; }
; __device__ __forceinline__ void row_rs8(float (&rs)[8], const float* ssq, int row0, int fq) {
;     ...
;     for (int i = 0; i < 8; ++i) p[i] = *(const f32x4*)(ssq + (size_t)(row0 + (i >> 2) * HALF + (i & 3) * 16) * 16 + 4 * fq);
; #pragma unroll
;     for (int i = 0; i < 8; ++i) { float s = (p[i][0] + p[i][1]) + (p[i][2] + p[i][3]); s += __shfl_xor(s, 16); s += __shfl_xor(s, 32); rs[i] = __builtin_amdgcn_rsqf(s * (1.0f / DMODEL) + RMS_EPS); }
;     __device__ __forceinline__ void operator()(const f32x4 (&acc)[2][2][4][2], const Unit& u, int wr, int wc, int fr, int fq) const {
;     ...
;             for (int m = 0; m < 4; ++m) { const int row = row0 + ai * HALF + m * 16; const float r = rs[ai * 4 + m];
;                 bf16_t* rowp = O + (size_t)row * ldc + col0;
; #pragma unroll
;                 for (int bj = 0; bj < 2; ++bj) { f32x4 v0 = acc[ai][bj][m][0] * r, v1 = acc[ai][bj][m][1] * r;
; #pragma unroll
;                     for (int e = 0; e < 4; ++e) { const float a = fmaxf(v0[e], 0.f), b = fmaxf(v1[e], 0.f); v0[e] = a * a; v1[e] = b * b; }
;                     *(u32x4*)(rowp + bj * HALF) = pack8(v0, v1); } }
	v_add_f32_e32 v176, v136, v137
	v_add_f32_e32 v177, v138, v139
	v_add_f32_e32 v176, v176, v177
	ds_bpermute_b32 v177, v174, v176
	s_waitcnt lgkmcnt(0)
	v_add_f32_e32 v176, v176, v177
	ds_bpermute_b32 v177, v175, v176
	v_add_u32_e32 v178, 0x40000, v172
	s_waitcnt lgkmcnt(0)
	v_add_f32_e32 v176, v176, v177
	v_fmamk_f32 v176, v176, 0x3a800000, v193
	v_rsq_f32_e32 v180, v176
	s_nop 0
	v_pk_mul_f32 v[92:93], v[92:93], v[180:181] op_sel_hi:[1,0]
	v_pk_mul_f32 v[94:95], v[94:95], v[180:181] op_sel_hi:[1,0]
	v_pk_mul_f32 v[88:89], v[88:89], v[180:181] op_sel_hi:[1,0]
	v_pk_mul_f32 v[90:91], v[90:91], v[180:181] op_sel_hi:[1,0]
	v_max_f32_e32 v92, 0, v92
	v_max_f32_e32 v93, 0, v93
	v_max_f32_e32 v94, 0, v94
	v_max_f32_e32 v95, 0, v95
	v_max_f32_e32 v88, 0, v88
	v_max_f32_e32 v89, 0, v89
	v_max_f32_e32 v90, 0, v90
	v_max_f32_e32 v91, 0, v91
	v_pk_mul_f32 v[92:93], v[92:93], v[92:93]
	v_pk_mul_f32 v[94:95], v[94:95], v[94:95]
	v_pk_mul_f32 v[88:89], v[88:89], v[88:89]
	v_pk_mul_f32 v[90:91], v[90:91], v[90:91]
	v_cvt_pk_bf16_f32 v92, v92, v93
	v_cvt_pk_bf16_f32 v93, v94, v95
	v_cvt_pk_bf16_f32 v94, v88, v89
	v_cvt_pk_bf16_f32 v95, v90, v91
	global_store_dwordx4 v178, v[92:95], s[0:1] nt
	v_pk_mul_f32 v[84:85], v[84:85], v[180:181] op_sel_hi:[1,0]
	v_pk_mul_f32 v[86:87], v[86:87], v[180:181] op_sel_hi:[1,0]
	v_pk_mul_f32 v[80:81], v[80:81], v[180:181] op_sel_hi:[1,0]
	v_pk_mul_f32 v[82:83], v[82:83], v[180:181] op_sel_hi:[1,0]
	v_max_f32_e32 v84, 0, v84
	v_max_f32_e32 v85, 0, v85
	v_max_f32_e32 v86, 0, v86
	v_max_f32_e32 v87, 0, v87
	v_max_f32_e32 v80, 0, v80
	v_max_f32_e32 v81, 0, v81
	v_max_f32_e32 v82, 0, v82
	v_max_f32_e32 v83, 0, v83
	v_pk_mul_f32 v[84:85], v[84:85], v[84:85]
	v_pk_mul_f32 v[86:87], v[86:87], v[86:87]
	v_pk_mul_f32 v[80:81], v[80:81], v[80:81]
	v_pk_mul_f32 v[82:83], v[82:83], v[82:83]
	v_cvt_pk_bf16_f32 v84, v84, v85
	v_cvt_pk_bf16_f32 v85, v86, v87
	v_cvt_pk_bf16_f32 v86, v80, v81
	v_cvt_pk_bf16_f32 v87, v82, v83
	global_store_dwordx4 v178, v[84:87], s[0:1] offset:256 nt
	s_waitcnt vmcnt(10)
	v_add_f32_e32 v176, v140, v141
	v_add_f32_e32 v177, v142, v143
	v_add_f32_e32 v176, v176, v177
	ds_bpermute_b32 v177, v174, v176
	s_waitcnt lgkmcnt(0)
	v_add_f32_e32 v176, v176, v177
	ds_bpermute_b32 v177, v175, v176
	v_add_u32_e32 v178, 0x60000, v172
	s_waitcnt lgkmcnt(0)
	v_add_f32_e32 v176, v176, v177
	v_fmamk_f32 v176, v176, 0x3a800000, v193
	v_rsq_f32_e32 v180, v176
	s_nop 0
	v_pk_mul_f32 v[76:77], v[76:77], v[180:181] op_sel_hi:[1,0]
	v_pk_mul_f32 v[78:79], v[78:79], v[180:181] op_sel_hi:[1,0]
	v_pk_mul_f32 v[72:73], v[72:73], v[180:181] op_sel_hi:[1,0]
	v_pk_mul_f32 v[74:75], v[74:75], v[180:181] op_sel_hi:[1,0]
	v_max_f32_e32 v76, 0, v76
	v_max_f32_e32 v77, 0, v77
	v_max_f32_e32 v78, 0, v78
	v_max_f32_e32 v79, 0, v79
	v_max_f32_e32 v72, 0, v72
	v_max_f32_e32 v73, 0, v73
	v_max_f32_e32 v74, 0, v74
	v_max_f32_e32 v75, 0, v75
	v_pk_mul_f32 v[76:77], v[76:77], v[76:77]
	v_pk_mul_f32 v[78:79], v[78:79], v[78:79]
	v_pk_mul_f32 v[72:73], v[72:73], v[72:73]
	v_pk_mul_f32 v[74:75], v[74:75], v[74:75]
	v_cvt_pk_bf16_f32 v76, v76, v77
	v_cvt_pk_bf16_f32 v77, v78, v79
	v_cvt_pk_bf16_f32 v78, v72, v73
	v_cvt_pk_bf16_f32 v79, v74, v75
	global_store_dwordx4 v178, v[76:79], s[0:1] nt
	v_pk_mul_f32 v[68:69], v[68:69], v[180:181] op_sel_hi:[1,0]
	v_pk_mul_f32 v[70:71], v[70:71], v[180:181] op_sel_hi:[1,0]
	v_pk_mul_f32 v[64:65], v[64:65], v[180:181] op_sel_hi:[1,0]
	v_pk_mul_f32 v[66:67], v[66:67], v[180:181] op_sel_hi:[1,0]
	v_max_f32_e32 v68, 0, v68
	v_max_f32_e32 v69, 0, v69
	v_max_f32_e32 v70, 0, v70
	v_max_f32_e32 v71, 0, v71
	v_max_f32_e32 v64, 0, v64
	v_max_f32_e32 v65, 0, v65
	v_max_f32_e32 v66, 0, v66
	v_max_f32_e32 v67, 0, v67
	v_pk_mul_f32 v[68:69], v[68:69], v[68:69]
	v_pk_mul_f32 v[70:71], v[70:71], v[70:71]
	v_pk_mul_f32 v[64:65], v[64:65], v[64:65]
	v_pk_mul_f32 v[66:67], v[66:67], v[66:67]
	v_cvt_pk_bf16_f32 v68, v68, v69
	v_cvt_pk_bf16_f32 v69, v70, v71
	v_cvt_pk_bf16_f32 v70, v64, v65
	v_cvt_pk_bf16_f32 v71, v66, v67
	global_store_dwordx4 v178, v[68:71], s[0:1] offset:256 nt
	s_waitcnt vmcnt(11)
	v_add_f32_e32 v176, v144, v145
	v_add_f32_e32 v177, v146, v147
	v_add_f32_e32 v176, v176, v177
	ds_bpermute_b32 v177, v174, v176
	s_waitcnt lgkmcnt(0)
	v_add_f32_e32 v176, v176, v177
	ds_bpermute_b32 v177, v175, v176
	v_add_u32_e32 v178, 0x100000, v172
	s_waitcnt lgkmcnt(0)
	v_add_f32_e32 v176, v176, v177
	v_fmamk_f32 v176, v176, 0x3a800000, v193
	v_rsq_f32_e32 v180, v176
	s_nop 0
	v_pk_mul_f32 v[60:61], v[60:61], v[180:181] op_sel_hi:[1,0]
	v_pk_mul_f32 v[62:63], v[62:63], v[180:181] op_sel_hi:[1,0]
	v_pk_mul_f32 v[56:57], v[56:57], v[180:181] op_sel_hi:[1,0]
	v_pk_mul_f32 v[58:59], v[58:59], v[180:181] op_sel_hi:[1,0]
	v_max_f32_e32 v60, 0, v60
	v_max_f32_e32 v61, 0, v61
	v_max_f32_e32 v62, 0, v62
	v_max_f32_e32 v63, 0, v63
	v_max_f32_e32 v56, 0, v56
	v_max_f32_e32 v57, 0, v57
	v_max_f32_e32 v58, 0, v58
	v_max_f32_e32 v59, 0, v59
	v_pk_mul_f32 v[60:61], v[60:61], v[60:61]
	v_pk_mul_f32 v[62:63], v[62:63], v[62:63]
	v_pk_mul_f32 v[56:57], v[56:57], v[56:57]
	v_pk_mul_f32 v[58:59], v[58:59], v[58:59]
	v_cvt_pk_bf16_f32 v60, v60, v61
	v_cvt_pk_bf16_f32 v61, v62, v63
	v_cvt_pk_bf16_f32 v62, v56, v57
	v_cvt_pk_bf16_f32 v63, v58, v59
	global_store_dwordx4 v178, v[60:63], s[0:1] nt
	v_pk_mul_f32 v[52:53], v[52:53], v[180:181] op_sel_hi:[1,0]
	v_pk_mul_f32 v[54:55], v[54:55], v[180:181] op_sel_hi:[1,0]
	v_pk_mul_f32 v[48:49], v[48:49], v[180:181] op_sel_hi:[1,0]
	v_pk_mul_f32 v[50:51], v[50:51], v[180:181] op_sel_hi:[1,0]
	v_max_f32_e32 v52, 0, v52
	v_max_f32_e32 v53, 0, v53
	v_max_f32_e32 v54, 0, v54
	v_max_f32_e32 v55, 0, v55
	v_max_f32_e32 v48, 0, v48
	v_max_f32_e32 v49, 0, v49
	v_max_f32_e32 v50, 0, v50
	v_max_f32_e32 v51, 0, v51
	v_pk_mul_f32 v[52:53], v[52:53], v[52:53]
	v_pk_mul_f32 v[54:55], v[54:55], v[54:55]
	v_pk_mul_f32 v[48:49], v[48:49], v[48:49]
	v_pk_mul_f32 v[50:51], v[50:51], v[50:51]
	v_cvt_pk_bf16_f32 v52, v52, v53
	v_cvt_pk_bf16_f32 v53, v54, v55
	v_cvt_pk_bf16_f32 v54, v48, v49
	v_cvt_pk_bf16_f32 v55, v50, v51
	global_store_dwordx4 v178, v[52:55], s[0:1] offset:256 nt
	s_waitcnt vmcnt(12)
; __device__ __forceinline__ u32x4 pack8(const f32x4 v0, const f32x4 v1) { u32x4 w; w.x = cvt_pk_bf16(v0[0], v0[1]); w.y = cvt_pk_bf16(v0[2], v0[3]); w.z = cvt_pk_bf16(v1[0], v1[1]); w.w = cvt_pk_bf16(v1[2], v1[3]); return w; }
; __device__ __forceinline__ void row_rs8(float (&rs)[8], const float* ssq, int row0, int fq) {
;     ...
;     for (int i = 0; i < 8; ++i) p[i] = *(const f32x4*)(ssq + (size_t)(row0 + (i >> 2) * HALF + (i & 3) * 16) * 16 + 4 * fq);
; #pragma unroll
;     for (int i = 0; i < 8; ++i) { float s = (p[i][0] + p[i][1]) + (p[i][2] + p[i][3]); s += __shfl_xor(s, 16); s += __shfl_xor(s, 32); rs[i] = __builtin_amdgcn_rsqf(s * (1.0f / DMODEL) + RMS_EPS); }
;     __device__ __forceinline__ void operator()(const f32x4 (&acc)[2][2][4][2], const Unit& u, int wr, int wc, int fr, int fq) const {
;     ...
;             for (int m = 0; m < 4; ++m) { const int row = row0 + ai * HALF + m * 16; const float r = rs[ai * 4 + m];
;                 bf16_t* rowp = O + (size_t)row * ldc + col0;
; #pragma unroll
;                 for (int bj = 0; bj < 2; ++bj) { f32x4 v0 = acc[ai][bj][m][0] * r, v1 = acc[ai][bj][m][1] * r;
; #pragma unroll
;                     for (int e = 0; e < 4; ++e) { const float a = fmaxf(v0[e], 0.f), b = fmaxf(v1[e], 0.f); v0[e] = a * a; v1[e] = b * b; }
;                     *(u32x4*)(rowp + bj * HALF) = pack8(v0, v1); } }
	v_add_f32_e32 v176, v148, v149
	v_add_f32_e32 v177, v150, v151
	v_add_f32_e32 v176, v176, v177
	ds_bpermute_b32 v177, v174, v176
	s_waitcnt lgkmcnt(0)
	v_add_f32_e32 v176, v176, v177
	ds_bpermute_b32 v177, v175, v176
	v_add_u32_e32 v178, 0x120000, v172
	s_waitcnt lgkmcnt(0)
	v_add_f32_e32 v176, v176, v177
	v_fmamk_f32 v176, v176, 0x3a800000, v193
	v_rsq_f32_e32 v180, v176
	s_nop 0
	v_pk_mul_f32 v[44:45], v[44:45], v[180:181] op_sel_hi:[1,0]
	v_pk_mul_f32 v[46:47], v[46:47], v[180:181] op_sel_hi:[1,0]
	v_pk_mul_f32 v[40:41], v[40:41], v[180:181] op_sel_hi:[1,0]
	v_pk_mul_f32 v[42:43], v[42:43], v[180:181] op_sel_hi:[1,0]
	v_max_f32_e32 v44, 0, v44
	v_max_f32_e32 v45, 0, v45
	v_max_f32_e32 v46, 0, v46
	v_max_f32_e32 v47, 0, v47
	v_max_f32_e32 v40, 0, v40
	v_max_f32_e32 v41, 0, v41
	v_max_f32_e32 v42, 0, v42
	v_max_f32_e32 v43, 0, v43
	v_pk_mul_f32 v[44:45], v[44:45], v[44:45]
	v_pk_mul_f32 v[46:47], v[46:47], v[46:47]
	v_pk_mul_f32 v[40:41], v[40:41], v[40:41]
	v_pk_mul_f32 v[42:43], v[42:43], v[42:43]
	v_cvt_pk_bf16_f32 v44, v44, v45
	v_cvt_pk_bf16_f32 v45, v46, v47
	v_cvt_pk_bf16_f32 v46, v40, v41
	v_cvt_pk_bf16_f32 v47, v42, v43
	global_store_dwordx4 v178, v[44:47], s[0:1] nt
	v_pk_mul_f32 v[36:37], v[36:37], v[180:181] op_sel_hi:[1,0]
	v_pk_mul_f32 v[38:39], v[38:39], v[180:181] op_sel_hi:[1,0]
	v_pk_mul_f32 v[32:33], v[32:33], v[180:181] op_sel_hi:[1,0]
	v_pk_mul_f32 v[34:35], v[34:35], v[180:181] op_sel_hi:[1,0]
	v_max_f32_e32 v36, 0, v36
	v_max_f32_e32 v37, 0, v37
	v_max_f32_e32 v38, 0, v38
	v_max_f32_e32 v39, 0, v39
	v_max_f32_e32 v32, 0, v32
	v_max_f32_e32 v33, 0, v33
	v_max_f32_e32 v34, 0, v34
	v_max_f32_e32 v35, 0, v35
	v_pk_mul_f32 v[36:37], v[36:37], v[36:37]
	v_pk_mul_f32 v[38:39], v[38:39], v[38:39]
	v_pk_mul_f32 v[32:33], v[32:33], v[32:33]
	v_pk_mul_f32 v[34:35], v[34:35], v[34:35]
	v_cvt_pk_bf16_f32 v36, v36, v37
	v_cvt_pk_bf16_f32 v37, v38, v39
	v_cvt_pk_bf16_f32 v38, v32, v33
	v_cvt_pk_bf16_f32 v39, v34, v35
	global_store_dwordx4 v178, v[36:39], s[0:1] offset:256 nt
	s_waitcnt vmcnt(13)
	v_add_f32_e32 v176, v164, v165
	v_add_f32_e32 v177, v166, v167
	v_add_f32_e32 v176, v176, v177
	ds_bpermute_b32 v177, v174, v176
	s_waitcnt lgkmcnt(0)
	v_add_f32_e32 v176, v176, v177
	ds_bpermute_b32 v177, v175, v176
	v_add_u32_e32 v178, 0x140000, v172
	s_waitcnt lgkmcnt(0)
	v_add_f32_e32 v176, v176, v177
	v_fmamk_f32 v176, v176, 0x3a800000, v193
	v_rsq_f32_e32 v180, v176
	s_nop 0
	v_pk_mul_f32 v[28:29], v[28:29], v[180:181] op_sel_hi:[1,0]
	v_pk_mul_f32 v[30:31], v[30:31], v[180:181] op_sel_hi:[1,0]
	v_pk_mul_f32 v[24:25], v[24:25], v[180:181] op_sel_hi:[1,0]
	v_pk_mul_f32 v[26:27], v[26:27], v[180:181] op_sel_hi:[1,0]
	v_max_f32_e32 v28, 0, v28
	v_max_f32_e32 v29, 0, v29
	v_max_f32_e32 v30, 0, v30
	v_max_f32_e32 v31, 0, v31
	v_max_f32_e32 v24, 0, v24
	v_max_f32_e32 v25, 0, v25
	v_max_f32_e32 v26, 0, v26
	v_max_f32_e32 v27, 0, v27
	v_pk_mul_f32 v[28:29], v[28:29], v[28:29]
	v_pk_mul_f32 v[30:31], v[30:31], v[30:31]
	v_pk_mul_f32 v[24:25], v[24:25], v[24:25]
	v_pk_mul_f32 v[26:27], v[26:27], v[26:27]
	v_cvt_pk_bf16_f32 v28, v28, v29
	v_cvt_pk_bf16_f32 v29, v30, v31
	v_cvt_pk_bf16_f32 v30, v24, v25
	v_cvt_pk_bf16_f32 v31, v26, v27
	global_store_dwordx4 v178, v[28:31], s[0:1] nt
	v_pk_mul_f32 v[20:21], v[20:21], v[180:181] op_sel_hi:[1,0]
	v_pk_mul_f32 v[22:23], v[22:23], v[180:181] op_sel_hi:[1,0]
	v_pk_mul_f32 v[16:17], v[16:17], v[180:181] op_sel_hi:[1,0]
	v_pk_mul_f32 v[18:19], v[18:19], v[180:181] op_sel_hi:[1,0]
	v_max_f32_e32 v20, 0, v20
	v_max_f32_e32 v21, 0, v21
	v_max_f32_e32 v22, 0, v22
	v_max_f32_e32 v23, 0, v23
	v_max_f32_e32 v16, 0, v16
	v_max_f32_e32 v17, 0, v17
	v_max_f32_e32 v18, 0, v18
	v_max_f32_e32 v19, 0, v19
	v_pk_mul_f32 v[20:21], v[20:21], v[20:21]
	v_pk_mul_f32 v[22:23], v[22:23], v[22:23]
	v_pk_mul_f32 v[16:17], v[16:17], v[16:17]
	v_pk_mul_f32 v[18:19], v[18:19], v[18:19]
	v_cvt_pk_bf16_f32 v20, v20, v21
	v_cvt_pk_bf16_f32 v21, v22, v23
	v_cvt_pk_bf16_f32 v22, v16, v17
	v_cvt_pk_bf16_f32 v23, v18, v19
	global_store_dwordx4 v178, v[20:23], s[0:1] offset:256 nt
	s_waitcnt vmcnt(14)
	v_add_f32_e32 v176, v168, v169
	v_add_f32_e32 v177, v170, v171
	v_add_f32_e32 v176, v176, v177
	ds_bpermute_b32 v177, v174, v176
	s_waitcnt lgkmcnt(0)
	v_add_f32_e32 v176, v176, v177
	ds_bpermute_b32 v177, v175, v176
	v_add_u32_e32 v178, 0x160000, v172
	s_waitcnt lgkmcnt(0)
	v_add_f32_e32 v176, v176, v177
	v_fmamk_f32 v176, v176, 0x3a800000, v193
	v_rsq_f32_e32 v180, v176
	s_nop 0
	v_pk_mul_f32 v[12:13], v[12:13], v[180:181] op_sel_hi:[1,0]
	v_pk_mul_f32 v[14:15], v[14:15], v[180:181] op_sel_hi:[1,0]
	v_pk_mul_f32 v[8:9], v[8:9], v[180:181] op_sel_hi:[1,0]
	v_pk_mul_f32 v[10:11], v[10:11], v[180:181] op_sel_hi:[1,0]
	v_max_f32_e32 v12, 0, v12
	v_max_f32_e32 v13, 0, v13
	v_max_f32_e32 v14, 0, v14
	v_max_f32_e32 v15, 0, v15
	v_max_f32_e32 v8, 0, v8
	v_max_f32_e32 v9, 0, v9
	v_max_f32_e32 v10, 0, v10
	v_max_f32_e32 v11, 0, v11
	v_pk_mul_f32 v[12:13], v[12:13], v[12:13]
	v_pk_mul_f32 v[14:15], v[14:15], v[14:15]
	v_pk_mul_f32 v[8:9], v[8:9], v[8:9]
	v_pk_mul_f32 v[10:11], v[10:11], v[10:11]
	v_cvt_pk_bf16_f32 v12, v12, v13
	v_cvt_pk_bf16_f32 v13, v14, v15
	v_cvt_pk_bf16_f32 v14, v8, v9
	v_cvt_pk_bf16_f32 v15, v10, v11
	global_store_dwordx4 v178, v[12:15], s[0:1] nt
	v_pk_mul_f32 v[4:5], v[4:5], v[180:181] op_sel_hi:[1,0]
	v_pk_mul_f32 v[6:7], v[6:7], v[180:181] op_sel_hi:[1,0]
	v_pk_mul_f32 v[0:1], v[0:1], v[180:181] op_sel_hi:[1,0]
	v_pk_mul_f32 v[2:3], v[2:3], v[180:181] op_sel_hi:[1,0]
	v_max_f32_e32 v4, 0, v4
	v_max_f32_e32 v5, 0, v5
	v_max_f32_e32 v6, 0, v6
	v_max_f32_e32 v7, 0, v7
	v_max_f32_e32 v0, 0, v0
	v_max_f32_e32 v1, 0, v1
	v_max_f32_e32 v2, 0, v2
	v_max_f32_e32 v3, 0, v3
	v_pk_mul_f32 v[4:5], v[4:5], v[4:5]
	v_pk_mul_f32 v[6:7], v[6:7], v[6:7]
	v_pk_mul_f32 v[0:1], v[0:1], v[0:1]
	v_pk_mul_f32 v[2:3], v[2:3], v[2:3]
	v_cvt_pk_bf16_f32 v4, v4, v5
	v_cvt_pk_bf16_f32 v5, v6, v7
	v_cvt_pk_bf16_f32 v6, v0, v1
	v_cvt_pk_bf16_f32 v7, v2, v3
	global_store_dwordx4 v178, v[4:7], s[0:1] offset:256 nt
	s_mov_b64 s[26:27], -1
	s_andn2_b64 vcc, exec, s[14:15]
	s_mov_b64 s[14:15], -1
	s_cbranch_vccnz .LBB0_601
	s_andn2_b64 vcc, exec, s[4:5]
	s_cbranch_vccnz .LBB0_600
	s_barrier
	s_branch .LBB0_600
